# wave 0 at s_setprio 3 while it runs the grid-barrier protocol beside the background conversion
# speedup vs baseline: 1.0028x; 1.0001x over previous
; __device__ __forceinline__ void xcd_barrier_cv(const XcdBarrier& b, Frame& F, const CvPtrs& P, int s, bool local) {
;     asm volatile("s_waitcnt vmcnt(0)" ::: "memory");
;     __syncthreads();
;     if (threadIdx.x < 64) { if (threadIdx.x == 0) { if (local) xcc_barrier_thread0(b); else xcd_barrier_thread0(b); } }
;     else if (cv_bg_share(s) >= 0 && cv_bg_share(s) < CV_BG_SHARES) cv_background(F, P, s);
;     __syncthreads();
.LBB0_16:
	s_setprio 0
	s_or_b64 exec, exec, s[4:5]
	s_waitcnt lgkmcnt(0)
	s_barrier

; __device__ __forceinline__ void xcd_barrier_cv(const XcdBarrier& b, Frame& F, const CvPtrs& P, int s, bool local) {
;     asm volatile("s_waitcnt vmcnt(0)" ::: "memory");
;     __syncthreads();
;     if (threadIdx.x < 64) { if (threadIdx.x == 0) { if (local) xcc_barrier_thread0(b); else xcd_barrier_thread0(b); } }
.LBB0_1016:
	s_setprio 3
	s_and_saveexec_b64 s[6:7], s[56:57]
	s_cbranch_execnz .LBB0_1017
	s_getpc_b64 s[98:99]
